# FF1 K-loop: LDS-DMA through buffer_load_dwordx4 lds with an SRD over the workspace and scalar tile offsets
# speedup vs baseline: 1.0028x; 1.0028x over previous
.LBB0_197:
	v_readlane_b32 s2, v237, 15
	s_waitcnt vmcnt(0)
	v_mov_b32_e32 v18, v190
	v_readlane_b32 s3, v237, 16
	s_movk_i32 s42, 0x400
	v_readfirstlane_b32 s31, v18
	s_movk_i32 s38, 0x400
	s_andn2_b64 vcc, exec, s[2:3]
	s_cbranch_vccnz .LBB0_219
	v_writelane_b32 v238, s92, 0
	v_writelane_b32 v238, s93, 1
	v_writelane_b32 v238, s94, 2
	v_writelane_b32 v238, s95, 3
	v_readlane_b32 s92, v237, 0
	v_readlane_b32 s93, v237, 1
	s_nop 4
	s_load_dwordx2 s[92:93], s[92:93], 0x80
	s_mov_b32 s94, -1
	s_mov_b32 s95, 0x20000
	s_waitcnt lgkmcnt(0)
	s_and_b32 s93, s93, 0xffff
	v_lshlrev_b32_e32 v0, 4, v18
	v_add_u32_e32 v2, 0x2000, v0
	s_waitcnt lgkmcnt(0)
	v_ashrrev_i32_e32 v3, 31, v2
	v_lshrrev_b32_e32 v3, 22, v3
	v_add_u32_e32 v3, v2, v3
	v_ashrrev_i32_e32 v3, 10, v3
	v_mul_i32_i24_e32 v4, 0x400, v3
	v_sub_u32_e32 v2, v2, v4
	v_lshrrev_b32_e32 v4, 4, v2
	v_bitop3_b32 v2, v4, v2, 32 bitop3:0x6c
	v_ashrrev_i32_e32 v4, 31, v2
	v_lshrrev_b32_e32 v4, 26, v4
	v_add_u32_e32 v4, v2, v4
	v_lshlrev_b32_e32 v6, 3, v3
	v_ashrrev_i32_e32 v5, 6, v4
	v_and_b32_e32 v6, -16, v6
	v_lshlrev_b32_e32 v3, 5, v3
	s_lshl_b32 s4, s97, 3
	v_readlane_b32 s27, v236, 12
	v_add_u32_e32 v6, v5, v6
	v_and_b32_e32 v20, 32, v3
	v_and_b32_e32 v3, 0xc0, v4
	s_or_b32 s54, s4, s27
	v_and_b32_e32 v5, 3, v5
	s_mov_b32 s27, 0x7fffffe0
	v_lshrrev_b32_e32 v7, 2, v6
	v_lshlrev_b32_e32 v8, 1, v6
	v_sub_u32_e32 v2, v2, v3
	v_and_or_b32 v5, v6, s27, v5
	v_and_b32_e32 v7, 4, v7
	v_and_b32_e32 v8, 24, v8
	v_ashrrev_i16_sdwa v2, v193, sext(v2) dst_sel:DWORD dst_unused:UNUSED_PAD src0_sel:DWORD src1_sel:BYTE_0
	v_or3_b32 v5, v5, v7, v8
	v_bfe_i32 v21, v2, 0, 16
	v_mul_lo_u32 v5, v5, s42
	v_add_u32_e32 v2, v20, v21
	v_mul_lo_u32 v22, v6, s38
	v_add_lshl_u32 v130, v5, v2, 1
	v_add_lshl_u32 v132, v2, v22, 1
	v_bfe_i32 v2, v18, 27, 1
	v_lshrrev_b32_e32 v2, 22, v2
	v_add_u32_e32 v2, v0, v2
	v_and_b32_e32 v2, 0xfffffc00, v2
	v_sub_u32_e32 v0, v0, v2
	v_lshrrev_b32_e32 v2, 4, v0
	v_ashrrev_i32_e32 v19, 31, v18
	v_bitop3_b32 v2, v2, v0, 32 bitop3:0x6c
	v_lshrrev_b32_e32 v4, 26, v19
	v_ashrrev_i32_e32 v0, 31, v2
	v_add_u32_e32 v4, v18, v4
	v_lshrrev_b32_e32 v0, 26, v0
	v_ashrrev_i32_e32 v4, 6, v4
	v_add_u32_e32 v3, v2, v0
	v_lshlrev_b32_e32 v5, 3, v4
	v_ashrrev_i32_e32 v0, 6, v3
	v_and_b32_e32 v5, -16, v5
	s_ashr_i32 s43, s42, 31
	v_add_u32_e32 v5, v0, v5
	v_readlane_b32 s40, v236, 24
	s_ashr_i32 s39, s38, 31
	s_lshl_b64 s[34:35], s[42:43], 9
	v_and_b32_e32 v0, 3, v0
	v_lshrrev_b32_e32 v6, 2, v5
	v_lshlrev_b32_e32 v7, 1, v5
	v_readlane_b32 s41, v236, 25
	s_lshl_b64 s[2:3], s[38:39], 8
	v_and_or_b32 v0, v5, s27, v0
	v_and_b32_e32 v6, 4, v6
	v_and_b32_e32 v7, 24, v7
	v_and_b32_e32 v3, 0xc0, v3
	v_mul_lo_u32 v24, v5, s38
	s_mul_i32 s27, s34, s41
	s_mul_hi_u32 s30, s34, s40
	s_lshr_b64 s[38:39], s[42:43], 23
	s_ashr_i32 s46, s31, 6
	v_or3_b32 v0, v0, v6, v7
	v_sub_u32_e32 v2, v2, v3
	s_ashr_i32 s55, s54, 31
	s_add_i32 s27, s30, s27
	s_mul_i32 s30, s38, s40
	s_lshl_b64 s[6:7], s[42:43], 8
	s_lshl_b32 s5, s46, 10
	v_mul_lo_u32 v6, v0, s42
	v_lshlrev_b32_e32 v0, 5, v4
	v_ashrrev_i16_sdwa v2, v193, sext(v2) dst_sel:DWORD dst_unused:UNUSED_PAD src0_sel:DWORD src1_sel:BYTE_0
	s_lshl_b64 s[28:29], s[54:55], 19
	s_add_i32 s27, s27, s30
	s_mul_i32 s30, s34, s40
	v_readlane_b32 s38, v235, 15
	v_and_b32_e32 v0, 32, v0
	v_bfe_i32 v23, v2, 0, 16
	s_add_u32 s58, s38, s30
	v_readlane_b32 s30, v235, 16
	v_add_u32_e32 v2, v0, v23
	s_addc_u32 s59, s30, s27
	s_add_i32 s27, s5, 0
	v_add_lshl_u32 v134, v6, v2, 1
	s_add_i32 m0, s27, 0x10000
	v_add_lshl_u32 v136, v2, v24, 1
	global_load_lds_dwordx4 v134, s[58:59]
	s_add_i32 m0, s27, 0x12000
	s_add_u32 s44, s58, s6
	global_load_lds_dwordx4 v130, s[58:59]
	s_addc_u32 s45, s59, s7
	s_add_i32 m0, s27, 0x14000
	v_mov_b32_e32 v2, 0
	global_load_lds_dwordx4 v134, s[44:45]
	s_add_i32 m0, s27, 0x16000
	s_add_u32 s56, s22, s28
	s_addc_u32 s57, s23, s29
	s_add_i32 s28, s27, 0x2000
	global_load_lds_dwordx4 v130, s[44:45]
	s_mov_b32 m0, s27
	s_add_u32 s38, s56, s2
	global_load_lds_dwordx4 v136, s[56:57]
	s_mov_b32 m0, s28
	s_addc_u32 s39, s57, s3
	s_add_i32 s29, s27, 0x4000
	global_load_lds_dwordx4 v132, s[56:57]
	s_mov_b32 m0, s29
	s_add_i32 s30, s27, 0x6000
	global_load_lds_dwordx4 v136, s[38:39]
	s_mov_b32 m0, s30
	s_cmpk_lt_u32 s31, 0x100
	global_load_lds_dwordx4 v132, s[38:39]
	s_cselect_b64 s[38:39], -1, 0
	s_cmpk_gt_u32 s31, 0xff
	v_mov_b32_e32 v3, 0
	v_mov_b32_e32 v4, 0
	v_mov_b32_e32 v5, 0
	v_mov_b32_e32 v6, 0
	v_mov_b32_e32 v7, 0
	v_mov_b32_e32 v8, 0
	v_mov_b32_e32 v9, 0
	v_mov_b32_e32 v10, 0
	v_mov_b32_e32 v11, 0
	v_mov_b32_e32 v12, 0
	v_mov_b32_e32 v13, 0
	v_mov_b32_e32 v14, 0
	v_mov_b32_e32 v15, 0
	v_mov_b32_e32 v16, 0
	v_mov_b32_e32 v17, 0
	s_cbranch_scc1 .LBB0_200
	s_lshl_b64 s[40:41], s[54:55], 14
	v_readlane_b32 s47, v236, 63
	s_add_u32 s40, s47, s40
	v_readlane_b32 s47, v235, 0
	s_addc_u32 s41, s47, s41
	v_lshlrev_b64 v[2:3], 6, v[18:19]
	v_lshl_add_u64 v[14:15], s[40:41], 0, v[2:3]
	global_load_dwordx4 v[2:5], v[14:15], off offset:48
	global_load_dwordx4 v[6:9], v[14:15], off offset:32
	global_load_dwordx4 v[10:13], v[14:15], off offset:16
	s_nop 0
	global_load_dwordx4 v[14:17], v[14:15], off

.LBB0_211:
	s_add_i32 s73, s58, 2
	s_add_u32 s74, s56, 0x80
	s_addc_u32 s59, s57, 0
	s_add_i32 s78, 0, 0x10000
	s_cmp_eq_u32 s63, s58
	s_cselect_b32 s59, s51, s59
	s_cselect_b32 s58, s55, s74
	v_add_u32_e32 v0, s78, v146
	s_cselect_b32 s75, s45, s72
	s_cselect_b32 s74, s44, s67
	s_add_i32 s80, 0, 0x14000
	ds_read_b128 v[148:151], v0
	ds_read_b128 v[152:155], v0 offset:1024
	ds_read_b128 v[156:159], v0 offset:2048
	ds_read_b128 v[160:163], v0 offset:3072
	v_add_u32_e32 v0, s80, v146
	ds_read_b128 v[164:167], v0
	ds_read_b128 v[168:171], v0 offset:1024
	ds_read_b128 v[172:175], v0 offset:2048
	ds_read_b128 v[176:179], v0 offset:3072
	s_sub_u32 s98, s56, s92
	s_mov_b32 m0, s31
	s_nop 0
	buffer_load_dwordx4 v136, s[92:95], s98 offen lds
	s_mov_b32 m0, s53
	s_nop 0
	buffer_load_dwordx4 v132, s[92:95], s98 offen lds
	s_add_i32 m0, s27, 0xc000
	s_nop 0
	buffer_load_dwordx4 v138, s[92:95], s98 offen lds
	s_add_i32 m0, s27, 0xe000
	s_nop 0
	buffer_load_dwordx4 v140, s[92:95], s98 offen lds
	ds_read_b128 v[180:183], v147
	ds_read_b128 v[184:187], v147 offset:1024
	ds_read_b128 v[200:203], v147 offset:2048
	ds_read_b128 v[204:207], v147 offset:3072
	ds_read_b128 v[208:211], v147 offset:4096
	ds_read_b128 v[212:215], v147 offset:5120
	ds_read_b128 v[216:219], v147 offset:6144
	ds_read_b128 v[220:223], v147 offset:7168
	s_waitcnt vmcnt(8)
	s_waitcnt lgkmcnt(0)
	s_barrier
	s_setprio 1
	s_waitcnt lgkmcnt(0)
	v_mfma_f32_16x16x32_bf16 v[122:125], v[148:151], v[180:183], v[122:125]
	v_mfma_f32_16x16x32_bf16 v[126:129], v[156:159], v[180:183], v[126:129]
	v_mfma_f32_16x16x32_bf16 v[110:113], v[148:151], v[200:203], v[110:113]
	v_mfma_f32_16x16x32_bf16 v[106:109], v[156:159], v[200:203], v[106:109]
	v_mfma_f32_16x16x32_bf16 v[94:97], v[148:151], v[208:211], v[94:97]
	v_mfma_f32_16x16x32_bf16 v[90:93], v[156:159], v[208:211], v[90:93]
	v_mfma_f32_16x16x32_bf16 v[78:81], v[148:151], v[216:219], v[78:81]
	v_mfma_f32_16x16x32_bf16 v[74:77], v[156:159], v[216:219], v[74:77]
	v_mfma_f32_16x16x32_bf16 v[122:125], v[152:155], v[184:187], v[122:125]
	v_mfma_f32_16x16x32_bf16 v[126:129], v[160:163], v[184:187], v[126:129]
	v_mfma_f32_16x16x32_bf16 v[110:113], v[152:155], v[204:207], v[110:113]
	v_mfma_f32_16x16x32_bf16 v[106:109], v[160:163], v[204:207], v[106:109]
	v_mfma_f32_16x16x32_bf16 v[94:97], v[152:155], v[212:215], v[94:97]
	v_mfma_f32_16x16x32_bf16 v[90:93], v[160:163], v[212:215], v[90:93]
	v_mfma_f32_16x16x32_bf16 v[78:81], v[152:155], v[220:223], v[78:81]
	v_mfma_f32_16x16x32_bf16 v[74:77], v[160:163], v[220:223], v[74:77]
	s_setprio 0
	s_setprio 1
	v_mfma_f32_16x16x32_bf16 v[118:121], v[164:167], v[180:183], v[118:121]
	v_mfma_f32_16x16x32_bf16 v[114:117], v[172:175], v[180:183], v[114:117]
	v_mfma_f32_16x16x32_bf16 v[102:105], v[164:167], v[200:203], v[102:105]
	v_mfma_f32_16x16x32_bf16 v[98:101], v[172:175], v[200:203], v[98:101]
	v_mfma_f32_16x16x32_bf16 v[86:89], v[164:167], v[208:211], v[86:89]
	v_mfma_f32_16x16x32_bf16 v[82:85], v[172:175], v[208:211], v[82:85]
	v_mfma_f32_16x16x32_bf16 v[70:73], v[164:167], v[216:219], v[70:73]
	v_mfma_f32_16x16x32_bf16 v[66:69], v[172:175], v[216:219], v[66:69]
	v_mfma_f32_16x16x32_bf16 v[118:121], v[168:171], v[184:187], v[118:121]
	v_mfma_f32_16x16x32_bf16 v[114:117], v[176:179], v[184:187], v[114:117]
	v_mfma_f32_16x16x32_bf16 v[102:105], v[168:171], v[204:207], v[102:105]
	v_mfma_f32_16x16x32_bf16 v[98:101], v[176:179], v[204:207], v[98:101]
	v_mfma_f32_16x16x32_bf16 v[86:89], v[168:171], v[212:215], v[86:89]
	v_mfma_f32_16x16x32_bf16 v[82:85], v[176:179], v[212:215], v[82:85]
	v_mfma_f32_16x16x32_bf16 v[70:73], v[168:171], v[220:223], v[70:73]
	v_mfma_f32_16x16x32_bf16 v[66:69], v[176:179], v[220:223], v[66:69]
	s_setprio 0
	s_barrier
	s_add_i32 s78, s78, s5
	s_sub_u32 s98, s74, s92
	s_mov_b32 m0, s78
	ds_read_b128 v[180:183], v147 offset:16384
	ds_read_b128 v[184:187], v147 offset:17408
	ds_read_b128 v[200:203], v147 offset:18432
	ds_read_b128 v[204:207], v147 offset:19456
	ds_read_b128 v[208:211], v147 offset:20480
	ds_read_b128 v[212:215], v147 offset:21504
	ds_read_b128 v[216:219], v147 offset:22528
	ds_read_b128 v[220:223], v147 offset:23552
	buffer_load_dwordx4 v134, s[92:95], s98 offen lds
	s_add_i32 m0, s78, 0x2000
	s_add_u32 s74, s74, s6
	s_addc_u32 s75, s75, s7
	buffer_load_dwordx4 v130, s[92:95], s98 offen lds
	s_add_i32 s78, s80, s5
	s_sub_u32 s99, s74, s92
	s_mov_b32 m0, s78
	s_add_u32 s100, s98, 0x80
	buffer_load_dwordx4 v134, s[92:95], s99 offen lds
	s_add_i32 m0, s78, 0x2000
	s_add_u32 s101, s99, 0x80
	buffer_load_dwordx4 v130, s[92:95], s99 offen lds
	s_waitcnt vmcnt(6)
	s_waitcnt lgkmcnt(0)
	s_barrier
	s_setprio 1
	s_waitcnt lgkmcnt(0)
	v_mfma_f32_16x16x32_bf16 v[62:65], v[148:151], v[180:183], v[62:65]
	v_mfma_f32_16x16x32_bf16 v[58:61], v[156:159], v[180:183], v[58:61]
	v_mfma_f32_16x16x32_bf16 v[46:49], v[148:151], v[200:203], v[46:49]
	v_mfma_f32_16x16x32_bf16 v[42:45], v[156:159], v[200:203], v[42:45]
	v_mfma_f32_16x16x32_bf16 v[30:33], v[148:151], v[208:211], v[30:33]
	v_mfma_f32_16x16x32_bf16 v[26:29], v[156:159], v[208:211], v[26:29]
	v_mfma_f32_16x16x32_bf16 v[14:17], v[148:151], v[216:219], v[14:17]
	v_mfma_f32_16x16x32_bf16 v[10:13], v[156:159], v[216:219], v[10:13]
	v_mfma_f32_16x16x32_bf16 v[62:65], v[152:155], v[184:187], v[62:65]
	v_mfma_f32_16x16x32_bf16 v[58:61], v[160:163], v[184:187], v[58:61]
	v_mfma_f32_16x16x32_bf16 v[46:49], v[152:155], v[204:207], v[46:49]
	v_mfma_f32_16x16x32_bf16 v[42:45], v[160:163], v[204:207], v[42:45]
	v_mfma_f32_16x16x32_bf16 v[30:33], v[152:155], v[212:215], v[30:33]
	v_mfma_f32_16x16x32_bf16 v[26:29], v[160:163], v[212:215], v[26:29]
	v_mfma_f32_16x16x32_bf16 v[14:17], v[152:155], v[220:223], v[14:17]
	v_mfma_f32_16x16x32_bf16 v[10:13], v[160:163], v[220:223], v[10:13]
	s_setprio 0
	s_setprio 1
	v_mfma_f32_16x16x32_bf16 v[54:57], v[164:167], v[180:183], v[54:57]
	v_mfma_f32_16x16x32_bf16 v[50:53], v[172:175], v[180:183], v[50:53]
	v_mfma_f32_16x16x32_bf16 v[38:41], v[164:167], v[200:203], v[38:41]
	v_mfma_f32_16x16x32_bf16 v[34:37], v[172:175], v[200:203], v[34:37]
	v_mfma_f32_16x16x32_bf16 v[22:25], v[164:167], v[208:211], v[22:25]
	v_mfma_f32_16x16x32_bf16 v[18:21], v[172:175], v[208:211], v[18:21]
	v_mfma_f32_16x16x32_bf16 v[6:9], v[164:167], v[216:219], v[6:9]
	v_mfma_f32_16x16x32_bf16 v[2:5], v[172:175], v[216:219], v[2:5]
	v_mfma_f32_16x16x32_bf16 v[54:57], v[168:171], v[184:187], v[54:57]
	v_mfma_f32_16x16x32_bf16 v[50:53], v[176:179], v[184:187], v[50:53]
	v_mfma_f32_16x16x32_bf16 v[38:41], v[168:171], v[204:207], v[38:41]
	v_mfma_f32_16x16x32_bf16 v[34:37], v[176:179], v[204:207], v[34:37]
	v_mfma_f32_16x16x32_bf16 v[22:25], v[168:171], v[212:215], v[22:25]
	v_mfma_f32_16x16x32_bf16 v[18:21], v[176:179], v[212:215], v[18:21]
	v_mfma_f32_16x16x32_bf16 v[6:9], v[168:171], v[220:223], v[6:9]
	v_mfma_f32_16x16x32_bf16 v[2:5], v[176:179], v[220:223], v[2:5]
	s_setprio 0
	s_barrier
	s_add_i32 s74, 0, 0x18000
	v_add_u32_e32 v0, s74, v146
	s_add_i32 s75, 0, 0x1c000
	ds_read_b128 v[148:151], v0
	ds_read_b128 v[152:155], v0 offset:1024
	ds_read_b128 v[156:159], v0 offset:2048
	ds_read_b128 v[160:163], v0 offset:3072
	v_add_u32_e32 v0, s75, v146
	ds_read_b128 v[164:167], v0
	ds_read_b128 v[168:171], v0 offset:1024
	ds_read_b128 v[172:175], v0 offset:2048
	ds_read_b128 v[176:179], v0 offset:3072
	s_sub_u32 s98, s58, s92
	s_mov_b32 m0, s27
	s_add_u32 s58, s58, s2
	buffer_load_dwordx4 v136, s[92:95], s98 offen lds
	s_mov_b32 m0, s28
	s_addc_u32 s59, s59, s3
	buffer_load_dwordx4 v132, s[92:95], s98 offen lds
	s_sub_u32 s99, s58, s92
	s_mov_b32 m0, s29
	s_nop 0
	buffer_load_dwordx4 v136, s[92:95], s99 offen lds
	s_mov_b32 m0, s30
	s_nop 0
	buffer_load_dwordx4 v132, s[92:95], s99 offen lds
	ds_read_b128 v[180:183], v147 offset:32768
	ds_read_b128 v[184:187], v147 offset:33792
	ds_read_b128 v[200:203], v147 offset:34816
	ds_read_b128 v[204:207], v147 offset:35840
	ds_read_b128 v[208:211], v147 offset:36864
	ds_read_b128 v[212:215], v147 offset:37888
	ds_read_b128 v[216:219], v147 offset:38912
	ds_read_b128 v[220:223], v147 offset:39936
	s_waitcnt vmcnt(8)
	s_waitcnt lgkmcnt(0)
	s_barrier
	s_setprio 1
	s_waitcnt lgkmcnt(0)
	v_mfma_f32_16x16x32_bf16 v[122:125], v[148:151], v[180:183], v[122:125]
	v_mfma_f32_16x16x32_bf16 v[126:129], v[156:159], v[180:183], v[126:129]
	v_mfma_f32_16x16x32_bf16 v[110:113], v[148:151], v[200:203], v[110:113]
	v_mfma_f32_16x16x32_bf16 v[106:109], v[156:159], v[200:203], v[106:109]
	v_mfma_f32_16x16x32_bf16 v[94:97], v[148:151], v[208:211], v[94:97]
	v_mfma_f32_16x16x32_bf16 v[90:93], v[156:159], v[208:211], v[90:93]
	v_mfma_f32_16x16x32_bf16 v[78:81], v[148:151], v[216:219], v[78:81]
	v_mfma_f32_16x16x32_bf16 v[74:77], v[156:159], v[216:219], v[74:77]
	v_mfma_f32_16x16x32_bf16 v[122:125], v[152:155], v[184:187], v[122:125]
	v_mfma_f32_16x16x32_bf16 v[126:129], v[160:163], v[184:187], v[126:129]
	v_mfma_f32_16x16x32_bf16 v[110:113], v[152:155], v[204:207], v[110:113]
	v_mfma_f32_16x16x32_bf16 v[106:109], v[160:163], v[204:207], v[106:109]
	v_mfma_f32_16x16x32_bf16 v[94:97], v[152:155], v[212:215], v[94:97]
	v_mfma_f32_16x16x32_bf16 v[90:93], v[160:163], v[212:215], v[90:93]
	v_mfma_f32_16x16x32_bf16 v[78:81], v[152:155], v[220:223], v[78:81]
	v_mfma_f32_16x16x32_bf16 v[74:77], v[160:163], v[220:223], v[74:77]
	s_setprio 0
	s_setprio 1
	v_mfma_f32_16x16x32_bf16 v[118:121], v[164:167], v[180:183], v[118:121]
	v_mfma_f32_16x16x32_bf16 v[114:117], v[172:175], v[180:183], v[114:117]
	v_mfma_f32_16x16x32_bf16 v[102:105], v[164:167], v[200:203], v[102:105]
	v_mfma_f32_16x16x32_bf16 v[98:101], v[172:175], v[200:203], v[98:101]
	v_mfma_f32_16x16x32_bf16 v[86:89], v[164:167], v[208:211], v[86:89]
	v_mfma_f32_16x16x32_bf16 v[82:85], v[172:175], v[208:211], v[82:85]
	v_mfma_f32_16x16x32_bf16 v[70:73], v[164:167], v[216:219], v[70:73]
	v_mfma_f32_16x16x32_bf16 v[66:69], v[172:175], v[216:219], v[66:69]
	v_mfma_f32_16x16x32_bf16 v[118:121], v[168:171], v[184:187], v[118:121]
	v_mfma_f32_16x16x32_bf16 v[114:117], v[176:179], v[184:187], v[114:117]
	v_mfma_f32_16x16x32_bf16 v[102:105], v[168:171], v[204:207], v[102:105]
	v_mfma_f32_16x16x32_bf16 v[98:101], v[176:179], v[204:207], v[98:101]
	v_mfma_f32_16x16x32_bf16 v[86:89], v[168:171], v[212:215], v[86:89]
	v_mfma_f32_16x16x32_bf16 v[82:85], v[176:179], v[212:215], v[82:85]
	v_mfma_f32_16x16x32_bf16 v[70:73], v[168:171], v[220:223], v[70:73]
	v_mfma_f32_16x16x32_bf16 v[66:69], v[176:179], v[220:223], v[66:69]
	s_setprio 0
	s_barrier
	s_add_i32 s58, s74, s5
	s_mov_b32 m0, s58
	ds_read_b128 v[180:183], v147 offset:49152
	ds_read_b128 v[184:187], v147 offset:50176
	ds_read_b128 v[200:203], v147 offset:51200
	ds_read_b128 v[204:207], v147 offset:52224
	ds_read_b128 v[208:211], v147 offset:53248
	ds_read_b128 v[212:215], v147 offset:54272
	ds_read_b128 v[216:219], v147 offset:55296
	ds_read_b128 v[220:223], v147 offset:56320
	buffer_load_dwordx4 v134, s[92:95], s100 offen lds
	s_add_i32 m0, s58, 0x2000
	s_add_i32 s58, s75, s5
	buffer_load_dwordx4 v130, s[92:95], s100 offen lds
	s_mov_b32 m0, s58
	s_nop 0
	buffer_load_dwordx4 v134, s[92:95], s101 offen lds
	s_add_i32 m0, s58, 0x2000
	s_nop 0
	buffer_load_dwordx4 v130, s[92:95], s101 offen lds
	s_waitcnt vmcnt(6)
	s_waitcnt lgkmcnt(0)
	s_barrier
	s_setprio 1
	s_waitcnt lgkmcnt(0)
	v_mfma_f32_16x16x32_bf16 v[62:65], v[148:151], v[180:183], v[62:65]
	v_mfma_f32_16x16x32_bf16 v[58:61], v[156:159], v[180:183], v[58:61]
	v_mfma_f32_16x16x32_bf16 v[46:49], v[148:151], v[200:203], v[46:49]
	v_mfma_f32_16x16x32_bf16 v[42:45], v[156:159], v[200:203], v[42:45]
	v_mfma_f32_16x16x32_bf16 v[30:33], v[148:151], v[208:211], v[30:33]
	v_mfma_f32_16x16x32_bf16 v[26:29], v[156:159], v[208:211], v[26:29]
	v_mfma_f32_16x16x32_bf16 v[14:17], v[148:151], v[216:219], v[14:17]
	v_mfma_f32_16x16x32_bf16 v[10:13], v[156:159], v[216:219], v[10:13]
	v_mfma_f32_16x16x32_bf16 v[62:65], v[152:155], v[184:187], v[62:65]
	v_mfma_f32_16x16x32_bf16 v[58:61], v[160:163], v[184:187], v[58:61]
	v_mfma_f32_16x16x32_bf16 v[46:49], v[152:155], v[204:207], v[46:49]
	v_mfma_f32_16x16x32_bf16 v[42:45], v[160:163], v[204:207], v[42:45]
	v_mfma_f32_16x16x32_bf16 v[30:33], v[152:155], v[212:215], v[30:33]
	v_mfma_f32_16x16x32_bf16 v[26:29], v[160:163], v[212:215], v[26:29]
	v_mfma_f32_16x16x32_bf16 v[14:17], v[152:155], v[220:223], v[14:17]
	v_mfma_f32_16x16x32_bf16 v[10:13], v[160:163], v[220:223], v[10:13]
	s_setprio 0
	s_setprio 1
	v_mfma_f32_16x16x32_bf16 v[54:57], v[164:167], v[180:183], v[54:57]
	v_mfma_f32_16x16x32_bf16 v[50:53], v[172:175], v[180:183], v[50:53]
	v_mfma_f32_16x16x32_bf16 v[38:41], v[164:167], v[200:203], v[38:41]
	v_mfma_f32_16x16x32_bf16 v[34:37], v[172:175], v[200:203], v[34:37]
	v_mfma_f32_16x16x32_bf16 v[22:25], v[164:167], v[208:211], v[22:25]
	v_mfma_f32_16x16x32_bf16 v[18:21], v[172:175], v[208:211], v[18:21]
	v_mfma_f32_16x16x32_bf16 v[6:9], v[164:167], v[216:219], v[6:9]
	v_mfma_f32_16x16x32_bf16 v[2:5], v[172:175], v[216:219], v[2:5]
	v_mfma_f32_16x16x32_bf16 v[54:57], v[168:171], v[184:187], v[54:57]
	v_mfma_f32_16x16x32_bf16 v[50:53], v[176:179], v[184:187], v[50:53]
	v_mfma_f32_16x16x32_bf16 v[38:41], v[168:171], v[204:207], v[38:41]
	v_mfma_f32_16x16x32_bf16 v[34:37], v[176:179], v[204:207], v[34:37]
	v_mfma_f32_16x16x32_bf16 v[22:25], v[168:171], v[212:215], v[22:25]
	v_mfma_f32_16x16x32_bf16 v[18:21], v[176:179], v[212:215], v[18:21]
	v_mfma_f32_16x16x32_bf16 v[6:9], v[168:171], v[220:223], v[6:9]
	v_mfma_f32_16x16x32_bf16 v[2:5], v[176:179], v[220:223], v[2:5]
	s_setprio 0
	s_barrier
	s_add_u32 s56, s56, 0x100
	s_addc_u32 s57, s57, 0
	s_add_u32 s67, s67, 0x100
	s_addc_u32 s72, s72, 0
	s_cmp_ge_i32 s73, s60
	s_mov_b32 s58, s73
	s_cbranch_scc0 .LBB0_211
	v_readlane_b32 s74, v236, 30
	v_readlane_b32 s75, v236, 31
	v_readlane_b32 s73, v236, 32
	s_mov_b32 s78, s76

.LBB0_218:
	s_waitcnt vmcnt(0)
	s_barrier
	v_readlane_b32 s92, v238, 0
	v_readlane_b32 s93, v238, 1
	v_readlane_b32 s94, v238, 2
	v_readlane_b32 s95, v238, 3

	.amdhsa_kernel _Z10fwd_kernel4Args
		.amdhsa_group_segment_fixed_size 0
		.amdhsa_private_segment_fixed_size 0
		.amdhsa_kernarg_size 400
		.amdhsa_user_sgpr_count 2
		.amdhsa_user_sgpr_dispatch_ptr 0
		.amdhsa_user_sgpr_queue_ptr 0
		.amdhsa_user_sgpr_kernarg_segment_ptr 1
		.amdhsa_user_sgpr_dispatch_id 0
		.amdhsa_user_sgpr_kernarg_preload_length 0
		.amdhsa_user_sgpr_kernarg_preload_offset 0
		.amdhsa_user_sgpr_private_segment_size 0
		.amdhsa_uses_dynamic_stack 0
		.amdhsa_enable_private_segment 0
		.amdhsa_system_sgpr_workgroup_id_x 1
		.amdhsa_system_sgpr_workgroup_id_y 0
		.amdhsa_system_sgpr_workgroup_id_z 0
		.amdhsa_system_sgpr_workgroup_info 0
		.amdhsa_system_vgpr_workitem_id 2
		.amdhsa_next_free_vgpr 239
		.amdhsa_next_free_sgpr 102
		.amdhsa_accum_offset 240
		.amdhsa_reserve_vcc 1
		.amdhsa_float_round_mode_32 0
		.amdhsa_float_round_mode_16_64 0
		.amdhsa_float_denorm_mode_32 3
		.amdhsa_float_denorm_mode_16_64 3
		.amdhsa_dx10_clamp 1
		.amdhsa_ieee_mode 1
		.amdhsa_fp16_overflow 0
		.amdhsa_tg_split 0
		.amdhsa_exception_fp_ieee_invalid_op 0
		.amdhsa_exception_fp_denorm_src 0
		.amdhsa_exception_fp_ieee_div_zero 0
		.amdhsa_exception_fp_ieee_overflow 0
		.amdhsa_exception_fp_ieee_underflow 0
		.amdhsa_exception_fp_ieee_inexact 0
		.amdhsa_exception_int_div_zero 0
	.end_amdhsa_kernel

amdhsa.kernels:
  - .agpr_count:     0
    .args:
      - .offset:         0
        .size:           144
        .value_kind:     by_value
      - .offset:         144
        .size:           4
        .value_kind:     hidden_block_count_x
      - .offset:         148
        .size:           4
        .value_kind:     hidden_block_count_y
      - .offset:         152
        .size:           4
        .value_kind:     hidden_block_count_z
      - .offset:         156
        .size:           2
        .value_kind:     hidden_group_size_x
      - .offset:         158
        .size:           2
        .value_kind:     hidden_group_size_y
      - .offset:         160
        .size:           2
        .value_kind:     hidden_group_size_z
      - .offset:         162
        .size:           2
        .value_kind:     hidden_remainder_x
      - .offset:         164
        .size:           2
        .value_kind:     hidden_remainder_y
      - .offset:         166
        .size:           2
        .value_kind:     hidden_remainder_z
      - .offset:         184
        .size:           8
        .value_kind:     hidden_global_offset_x
      - .offset:         192
        .size:           8
        .value_kind:     hidden_global_offset_y
      - .offset:         200
        .size:           8
        .value_kind:     hidden_global_offset_z
      - .offset:         208
        .size:           2
        .value_kind:     hidden_grid_dims
      - .offset:         232
        .size:           8
        .value_kind:     hidden_multigrid_sync_arg
      - .offset:         264
        .size:           4
        .value_kind:     hidden_dynamic_lds_size
    .group_segment_fixed_size: 0
    .kernarg_segment_align: 8
    .kernarg_segment_size: 400
    .language:       OpenCL C
    .language_version:
      - 2
      - 0
    .max_flat_workgroup_size: 512
    .name:           _Z10fwd_kernel4Args
    .private_segment_fixed_size: 0
    .sgpr_count:     108
    .sgpr_spill_count: 216
    .symbol:         _Z10fwd_kernel4Args.kd
    .uniform_work_group_size: 1
    .uses_dynamic_stack: false
    .vgpr_count:     239
    .vgpr_spill_count: 0
    .wavefront_size: 64
